# gdn_prep silu uses v_rcp_f32 + one Newton step instead of the IEEE division sequence (same as the 6a/6c epilogues)
# speedup vs baseline: 1.1602x; 1.0001x over previous
; DI float siluf_(float x) { return x / (1.f + __expf(-x)); }
; DI void phase_gdn_prep(const Ctx& c) {
;     ...
;       const int col = part * 512 + lane * 8;
;       float cur[8], prv[8], nxt[8], v[8];
;       unpack8(*(const uint4*)(P + (size_t)tok * 1536 + col), cur);
;       if (n > 0) unpack8(*(const uint4*)(P + (size_t)(tok - 1) * 1536 + col), prv);
;       else { for (int e = 0; e < 8; ++e) prv[e] = 0.f; }
;       if (n < L - 1) unpack8(*(const uint4*)(P + (size_t)(tok + 1) * 1536 + col), nxt);
;       else { for (int e = 0; e < 8; ++e) nxt[e] = 0.f; }
;       float ss = 0.f;
; #pragma unroll
;       for (int e = 0; e < 8; ++e) {
;         const float x = prv[e] * cw[col + e] + cur[e] * cw[1536 + col + e] + nxt[e] * cw[3072 + col + e];
;         v[e] = siluf_(x); ss += v[e] * v[e];
;       }
;       if (part < 2) {
;         ss += __shfl_xor(ss, 1); ss += __shfl_xor(ss, 2); ss += __shfl_xor(ss, 4); ss += __shfl_xor(ss, 8);
;         float inv = rsqrtf(ss + EPS);
;         if (part == 0) inv *= 0.08838834764831845f;
; #pragma unroll
;         for (int e = 0; e < 8; ++e) v[e] *= inv;
;       }
;       bf16* dst = (bf16*)(c.ws + OFF_GQ + (size_t)part * SZ_T512) + (size_t)tok * 512 + lane * 8;
;       *(uint4*)dst = pack8(v);
.LBB0_308:
	s_or_b64 exec, exec, s[10:11]
	global_load_dwordx4 v[68:71], v[20:21], off offset:16
	global_load_dwordx4 v[72:75], v[20:21], off
	global_load_dwordx4 v[76:79], v[18:19], off offset:16
	global_load_dwordx4 v[80:83], v[18:19], off
	global_load_dwordx4 v[84:87], v[22:23], off offset:16
	global_load_dwordx4 v[88:91], v[22:23], off
	s_waitcnt vmcnt(0)
	v_lshlrev_b32_e32 v50, 16, v230
	v_and_b32_e32 v51, 0xffff0000, v230
	v_lshlrev_b32_e32 v52, 16, v231
	v_and_b32_e32 v53, 0xffff0000, v231
	v_lshlrev_b32_e32 v54, 16, v232
	v_and_b32_e32 v55, 0xffff0000, v232
	v_lshlrev_b32_e32 v56, 16, v233
	v_and_b32_e32 v57, 0xffff0000, v233
	v_lshlrev_b32_e32 v48, 16, v234
	v_and_b32_e32 v49, 0xffff0000, v234
	v_lshlrev_b32_e32 v58, 16, v235
	v_and_b32_e32 v59, 0xffff0000, v235
	v_lshlrev_b32_e32 v60, 16, v236
	v_and_b32_e32 v61, 0xffff0000, v236
	v_lshlrev_b32_e32 v62, 16, v237
	v_and_b32_e32 v63, 0xffff0000, v237
	v_lshlrev_b32_e32 v94, 16, v4
	v_and_b32_e32 v95, 0xffff0000, v4
	v_lshlrev_b32_e32 v4, 16, v5
	v_and_b32_e32 v5, 0xffff0000, v5
	v_lshlrev_b32_e32 v92, 16, v3
	v_and_b32_e32 v93, 0xffff0000, v3
	v_lshlrev_b32_e32 v64, 16, v2
	v_and_b32_e32 v65, 0xffff0000, v2
	v_pk_mul_f32 v[4:5], v[70:71], v[4:5]
	v_pk_mul_f32 v[68:69], v[68:69], v[94:95]
	v_pk_fma_f32 v[4:5], v[56:57], v[78:79], v[4:5]
	v_pk_mul_f32 v[70:71], v[74:75], v[92:93]
	v_pk_fma_f32 v[4:5], v[62:63], v[86:87], v[4:5]
	v_pk_fma_f32 v[54:55], v[54:55], v[76:77], v[68:69]
	v_pk_fma_f32 v[52:53], v[52:53], v[82:83], v[70:71]
	v_mul_f32_e32 v3, 0xbfb8aa3b, v4
	v_mul_f32_e32 v7, 0xbfb8aa3b, v5
	v_pk_fma_f32 v[54:55], v[60:61], v[84:85], v[54:55]
	v_pk_fma_f32 v[52:53], v[58:59], v[90:91], v[52:53]
	v_exp_f32_e32 v56, v3
	v_exp_f32_e32 v57, v7
	v_mul_f32_e32 v58, 0xbfb8aa3b, v54
	v_mul_f32_e32 v59, 0xbfb8aa3b, v55
	v_mul_f32_e32 v60, 0xbfb8aa3b, v52
	v_mul_f32_e32 v61, 0xbfb8aa3b, v53
	v_exp_f32_e32 v58, v58
	v_exp_f32_e32 v59, v59
	v_exp_f32_e32 v60, v60
	v_exp_f32_e32 v61, v61
	v_pk_add_f32 v[2:3], v[56:57], 1.0 op_sel_hi:[1,0]
	v_pk_add_f32 v[56:57], v[58:59], 1.0 op_sel_hi:[1,0]
	v_pk_add_f32 v[58:59], v[60:61], 1.0 op_sel_hi:[1,0]
	v_min_f32_e32 v230, 0x7f7fffff, v3
	v_rcp_f32_e32 v231, v230
	s_nop 0
	v_fma_f32 v232, -v230, v231, 1.0
	v_fma_f32 v231, v232, v231, v231
	v_mul_f32_e32 v61, v5, v231
	v_min_f32_e32 v230, 0x7f7fffff, v2
	v_rcp_f32_e32 v231, v230
	s_nop 0
	v_fma_f32 v232, -v230, v231, 1.0
	v_fma_f32 v231, v232, v231, v231
	v_mul_f32_e32 v60, v4, v231
	v_min_f32_e32 v230, 0x7f7fffff, v57
	v_rcp_f32_e32 v231, v230
	s_nop 0
	v_fma_f32 v232, -v230, v231, 1.0
	v_fma_f32 v231, v232, v231, v231
	v_mul_f32_e32 v55, v55, v231
	v_min_f32_e32 v230, 0x7f7fffff, v56
	v_rcp_f32_e32 v231, v230
	s_nop 0
	v_fma_f32 v232, -v230, v231, 1.0
	v_fma_f32 v231, v232, v231, v231
	v_mul_f32_e32 v54, v54, v231
	v_min_f32_e32 v230, 0x7f7fffff, v59
	v_rcp_f32_e32 v231, v230
	s_nop 0
	v_fma_f32 v232, -v230, v231, 1.0
	v_fma_f32 v231, v232, v231, v231
	v_mul_f32_e32 v53, v53, v231
	v_pk_mul_f32 v[2:3], v[72:73], v[64:65]
	v_pk_fma_f32 v[2:3], v[50:51], v[80:81], v[2:3]
	v_pk_fma_f32 v[48:49], v[48:49], v[88:89], v[2:3]
	v_mul_f32_e32 v2, 0xbfb8aa3b, v48
	v_mul_f32_e32 v3, 0xbfb8aa3b, v49
	v_exp_f32_e32 v2, v2
	v_exp_f32_e32 v3, v3
	v_pk_mul_f32 v[56:57], v[54:55], v[54:55]
	v_pk_add_f32 v[50:51], v[2:3], 1.0 op_sel_hi:[1,0]
	v_min_f32_e32 v230, 0x7f7fffff, v58
	v_rcp_f32_e32 v231, v230
	s_nop 0
	v_fma_f32 v232, -v230, v231, 1.0
	v_fma_f32 v231, v232, v231, v231
	v_mul_f32_e32 v52, v52, v231
	global_load_dwordx4 v[2:5], v[44:45], off offset:1024
	v_min_f32_e32 v230, 0x7f7fffff, v51
	v_rcp_f32_e32 v231, v230
	s_nop 0
	v_fma_f32 v232, -v230, v231, 1.0
	v_fma_f32 v231, v232, v231, v231
	v_mul_f32_e32 v51, v49, v231
	v_pk_mul_f32 v[58:59], v[52:53], v[52:53]
	v_min_f32_e32 v230, 0x7f7fffff, v50
	v_rcp_f32_e32 v231, v230
	s_nop 0
	v_fma_f32 v232, -v230, v231, 1.0
	v_fma_f32 v231, v232, v231, v231
	v_mul_f32_e32 v50, v48, v231
	v_pk_mul_f32 v[48:49], v[50:51], v[50:51]
	v_pk_mul_f32 v[62:63], v[60:61], v[60:61]
	v_add_f32_e32 v7, v48, v49
	v_add_f32_e32 v7, v7, v58
	v_add_f32_e32 v7, v7, v59
	v_add_f32_e32 v7, v7, v56
	v_add_f32_e32 v7, v7, v57
	v_add_f32_e32 v7, v7, v62
	v_add_f32_e32 v7, v7, v63
	ds_bpermute_b32 v48, v9, v7
	s_mov_b32 s10, 0x800000
	s_waitcnt lgkmcnt(0)
	v_add_f32_e32 v7, v7, v48
	ds_bpermute_b32 v48, v11, v7
	s_waitcnt lgkmcnt(0)
	v_add_f32_e32 v7, v7, v48
	ds_bpermute_b32 v48, v66, v7
	s_waitcnt lgkmcnt(0)
	v_add_f32_e32 v7, v7, v48
	ds_bpermute_b32 v48, v67, v7
	s_waitcnt lgkmcnt(0)
	v_add_f32_e32 v7, v7, v48
	v_add_f32_e32 v7, 0x358637bd, v7
	v_mul_f32_e32 v48, 0x4b800000, v7
	v_cmp_gt_f32_e32 vcc, s10, v7
	s_nop 1
	v_cndmask_b32_e32 v7, v7, v48, vcc
	v_rsq_f32_e32 v58, v7
	v_ashrrev_i32_e32 v7, 31, v6
	v_lshlrev_b64 v[48:49], 10, v[6:7]
	v_lshl_add_u64 v[56:57], v[34:35], 0, v[48:49]
	v_mul_f32_e32 v59, 0x45800000, v58
	v_cndmask_b32_e32 v58, v58, v59, vcc
	v_mul_f32_e32 v58, 0x3db504f3, v58
	v_pk_mul_f32 v[60:61], v[60:61], v[58:59] op_sel_hi:[1,0]
	v_pk_mul_f32 v[54:55], v[54:55], v[58:59] op_sel_hi:[1,0]
	v_pk_mul_f32 v[52:53], v[52:53], v[58:59] op_sel_hi:[1,0]
	v_pk_mul_f32 v[50:51], v[50:51], v[58:59] op_sel_hi:[1,0]
	v_mov_b32_e32 v58, 0
	v_cvt_pk_bf16_f32 v50, v50, v51
	v_cvt_pk_bf16_f32 v51, v52, v53
	v_cvt_pk_bf16_f32 v52, v54, v55
	v_cvt_pk_bf16_f32 v53, v60, v61
	global_store_dwordx4 v[56:57], v[50:53], off
	v_mov_b32_e32 v54, 0
	v_mov_b32_e32 v55, 0
	v_mov_b32_e32 v50, 0
	v_mov_b32_e32 v52, 0
	v_mov_b32_e32 v53, 0
	v_mov_b32_e32 v56, 0
	v_mov_b32_e32 v57, 0
	v_mov_b32_e32 v59, 0
	v_mov_b32_e32 v230, 0
	v_mov_b32_e32 v231, 0
	v_mov_b32_e32 v232, 0
	v_mov_b32_e32 v233, 0
	v_mov_b32_e32 v234, 0
	v_mov_b32_e32 v235, 0
	v_mov_b32_e32 v236, 0
	v_mov_b32_e32 v237, 0
	s_and_saveexec_b64 s[10:11], s[6:7]
	s_cbranch_execz .LBB0_310
	v_lshl_add_u64 v[52:53], v[42:43], 0, v[0:1]
	global_load_dwordx4 v[230:233], v[52:53], off offset:1024

; DI float siluf_(float x) { return x / (1.f + __expf(-x)); }
; DI void phase_gdn_prep(const Ctx& c) {
;     ...
;       const int col = part * 512 + lane * 8;
;       float cur[8], prv[8], nxt[8], v[8];
;       unpack8(*(const uint4*)(P + (size_t)tok * 1536 + col), cur);
;       if (n > 0) unpack8(*(const uint4*)(P + (size_t)(tok - 1) * 1536 + col), prv);
;       else { for (int e = 0; e < 8; ++e) prv[e] = 0.f; }
;       if (n < L - 1) unpack8(*(const uint4*)(P + (size_t)(tok + 1) * 1536 + col), nxt);
;       else { for (int e = 0; e < 8; ++e) nxt[e] = 0.f; }
;       float ss = 0.f;
; #pragma unroll
;       for (int e = 0; e < 8; ++e) {
;         const float x = prv[e] * cw[col + e] + cur[e] * cw[1536 + col + e] + nxt[e] * cw[3072 + col + e];
;         v[e] = siluf_(x); ss += v[e] * v[e];
;       }
;       if (part < 2) {
;         ss += __shfl_xor(ss, 1); ss += __shfl_xor(ss, 2); ss += __shfl_xor(ss, 4); ss += __shfl_xor(ss, 8);
;         float inv = rsqrtf(ss + EPS);
;         if (part == 0) inv *= 0.08838834764831845f;
; #pragma unroll
;         for (int e = 0; e < 8; ++e) v[e] *= inv;
;       }
;       bf16* dst = (bf16*)(c.ws + OFF_GQ + (size_t)part * SZ_T512) + (size_t)tok * 512 + lane * 8;
;       *(uint4*)dst = pack8(v);
.LBB0_312:
	s_or_b64 exec, exec, s[10:11]
	global_load_dwordx4 v[68:71], v[24:25], off offset:16
	global_load_dwordx4 v[72:75], v[24:25], off
	global_load_dwordx4 v[76:79], v[18:19], off offset:2064
	global_load_dwordx4 v[80:83], v[18:19], off offset:2048
	global_load_dwordx4 v[84:87], v[26:27], off offset:16
	global_load_dwordx4 v[88:91], v[26:27], off
	s_waitcnt vmcnt(7)
	v_lshlrev_b32_e32 v96, 16, v4
	v_and_b32_e32 v97, 0xffff0000, v4
	v_lshlrev_b32_e32 v4, 16, v5
	v_and_b32_e32 v5, 0xffff0000, v5
	v_lshlrev_b32_e32 v94, 16, v3
	v_and_b32_e32 v95, 0xffff0000, v3
	v_lshlrev_b32_e32 v92, 16, v2
	v_and_b32_e32 v93, 0xffff0000, v2
	s_waitcnt vmcnt(5)
	v_lshlrev_b32_e32 v52, 16, v230
	v_and_b32_e32 v53, 0xffff0000, v230
	v_lshlrev_b32_e32 v54, 16, v231
	v_and_b32_e32 v55, 0xffff0000, v231
	v_lshlrev_b32_e32 v56, 16, v232
	v_and_b32_e32 v57, 0xffff0000, v232
	v_lshlrev_b32_e32 v58, 16, v233
	v_and_b32_e32 v59, 0xffff0000, v233
	v_lshlrev_b32_e32 v50, 16, v234
	v_and_b32_e32 v51, 0xffff0000, v234
	v_lshlrev_b32_e32 v60, 16, v235
	v_and_b32_e32 v61, 0xffff0000, v235
	v_lshlrev_b32_e32 v62, 16, v236
	v_and_b32_e32 v63, 0xffff0000, v236
	v_lshlrev_b32_e32 v64, 16, v237
	v_and_b32_e32 v65, 0xffff0000, v237
	v_pk_mul_f32 v[4:5], v[70:71], v[4:5]
	v_pk_mul_f32 v[68:69], v[68:69], v[96:97]
	s_waitcnt vmcnt(4)
	v_pk_mul_f32 v[70:71], v[74:75], v[94:95]
	s_waitcnt vmcnt(3)
	v_pk_fma_f32 v[4:5], v[58:59], v[78:79], v[4:5]
	v_pk_fma_f32 v[56:57], v[56:57], v[76:77], v[68:69]
	s_waitcnt vmcnt(2)
	v_pk_fma_f32 v[54:55], v[54:55], v[82:83], v[70:71]
	s_waitcnt vmcnt(1)
	v_pk_fma_f32 v[4:5], v[64:65], v[86:87], v[4:5]
	v_pk_fma_f32 v[56:57], v[62:63], v[84:85], v[56:57]
	s_waitcnt vmcnt(0)
	v_pk_fma_f32 v[54:55], v[60:61], v[90:91], v[54:55]
	v_mul_f32_e32 v3, 0xbfb8aa3b, v4
	v_mul_f32_e32 v59, 0xbfb8aa3b, v5
	v_mul_f32_e32 v60, 0xbfb8aa3b, v56
	v_mul_f32_e32 v61, 0xbfb8aa3b, v57
	v_mul_f32_e32 v62, 0xbfb8aa3b, v54
	v_mul_f32_e32 v63, 0xbfb8aa3b, v55
	v_exp_f32_e32 v58, v3
	v_exp_f32_e32 v59, v59
	v_exp_f32_e32 v60, v60
	v_exp_f32_e32 v61, v61
	v_exp_f32_e32 v62, v62
	v_exp_f32_e32 v63, v63
	v_pk_add_f32 v[2:3], v[58:59], 1.0 op_sel_hi:[1,0]
	v_pk_add_f32 v[58:59], v[60:61], 1.0 op_sel_hi:[1,0]
	v_pk_add_f32 v[60:61], v[62:63], 1.0 op_sel_hi:[1,0]
	v_min_f32_e32 v230, 0x7f7fffff, v3
	v_rcp_f32_e32 v231, v230
	s_nop 0
	v_fma_f32 v232, -v230, v231, 1.0
	v_fma_f32 v231, v232, v231, v231
	v_mul_f32_e32 v3, v5, v231
	v_min_f32_e32 v230, 0x7f7fffff, v59
	v_rcp_f32_e32 v231, v230
	s_nop 0
	v_fma_f32 v232, -v230, v231, 1.0
	v_fma_f32 v231, v232, v231, v231
	v_mul_f32_e32 v57, v57, v231
	v_min_f32_e32 v230, 0x7f7fffff, v61
	v_rcp_f32_e32 v231, v230
	s_nop 0
	v_fma_f32 v232, -v230, v231, 1.0
	v_fma_f32 v231, v232, v231, v231
	v_mul_f32_e32 v55, v55, v231
	v_pk_mul_f32 v[62:63], v[72:73], v[92:93]
	v_pk_fma_f32 v[52:53], v[52:53], v[80:81], v[62:63]
	v_min_f32_e32 v230, 0x7f7fffff, v58
	v_rcp_f32_e32 v231, v230
	s_nop 0
	v_fma_f32 v232, -v230, v231, 1.0
	v_fma_f32 v231, v232, v231, v231
	v_mul_f32_e32 v56, v56, v231
	v_pk_fma_f32 v[50:51], v[50:51], v[88:89], v[52:53]
	v_mul_f32_e32 v52, 0xbfb8aa3b, v50
	v_mul_f32_e32 v53, 0xbfb8aa3b, v51
	v_exp_f32_e32 v52, v52
	v_exp_f32_e32 v53, v53
	s_nop 0
	v_pk_add_f32 v[52:53], v[52:53], 1.0 op_sel_hi:[1,0]
	v_min_f32_e32 v230, 0x7f7fffff, v60
	v_rcp_f32_e32 v231, v230
	s_nop 0
	v_fma_f32 v232, -v230, v231, 1.0
	v_fma_f32 v231, v232, v231, v231
	v_mul_f32_e32 v54, v54, v231
	v_min_f32_e32 v230, 0x7f7fffff, v53
	v_rcp_f32_e32 v231, v230
	s_nop 0
	v_fma_f32 v232, -v230, v231, 1.0
	v_fma_f32 v231, v232, v231, v231
	v_mul_f32_e32 v51, v51, v231
	v_pk_mul_f32 v[60:61], v[54:55], v[54:55]
	v_min_f32_e32 v230, 0x7f7fffff, v52
	v_rcp_f32_e32 v231, v230
	s_nop 0
	v_fma_f32 v232, -v230, v231, 1.0
	v_fma_f32 v231, v232, v231, v231
	v_mul_f32_e32 v50, v50, v231
	v_pk_mul_f32 v[52:53], v[50:51], v[50:51]
	v_pk_mul_f32 v[58:59], v[56:57], v[56:57]
	v_add_f32_e32 v52, v52, v53
	v_add_f32_e32 v52, v52, v60
	v_add_f32_e32 v52, v52, v61
	v_min_f32_e32 v230, 0x7f7fffff, v2
	v_rcp_f32_e32 v231, v230
	s_nop 0
	v_fma_f32 v232, -v230, v231, 1.0
	v_fma_f32 v231, v232, v231, v231
	v_mul_f32_e32 v2, v4, v231
	v_add_f32_e32 v52, v52, v58
	v_pk_mul_f32 v[4:5], v[2:3], v[2:3]
	v_add_f32_e32 v52, v52, v59
	v_add_f32_e32 v4, v52, v4
	v_add_f32_e32 v4, v4, v5
	ds_bpermute_b32 v5, v9, v4
	s_mov_b32 s10, 0x800000
	v_lshl_add_u64 v[52:53], v[36:37], 0, v[48:49]
	s_waitcnt lgkmcnt(0)
	v_add_f32_e32 v4, v4, v5
	ds_bpermute_b32 v5, v11, v4
	s_waitcnt lgkmcnt(0)
	v_add_f32_e32 v4, v4, v5
	ds_bpermute_b32 v5, v66, v4
	s_waitcnt lgkmcnt(0)
	v_add_f32_e32 v4, v4, v5
	ds_bpermute_b32 v5, v67, v4
	s_waitcnt lgkmcnt(0)
	v_add_f32_e32 v4, v4, v5
	v_add_f32_e32 v4, 0x358637bd, v4
	v_mul_f32_e32 v5, 0x4b800000, v4
	v_cmp_gt_f32_e32 vcc, s10, v4
	s_nop 1
	v_cndmask_b32_e32 v4, v4, v5, vcc
	v_rsq_f32_e32 v4, v4
	s_nop 0
	v_mul_f32_e32 v5, 0x45800000, v4
	v_cndmask_b32_e32 v4, v4, v5, vcc
	v_pk_mul_f32 v[50:51], v[50:51], v[4:5] op_sel_hi:[1,0]
	v_pk_mul_f32 v[54:55], v[54:55], v[4:5] op_sel_hi:[1,0]
	v_pk_mul_f32 v[56:57], v[56:57], v[4:5] op_sel_hi:[1,0]
	v_pk_mul_f32 v[58:59], v[2:3], v[4:5] op_sel_hi:[1,0]
	v_cvt_pk_bf16_f32 v2, v50, v51
	v_cvt_pk_bf16_f32 v3, v54, v55
	v_cvt_pk_bf16_f32 v4, v56, v57
	v_cvt_pk_bf16_f32 v5, v58, v59
	global_store_dwordx4 v[52:53], v[2:5], off
	global_load_dwordx4 v[2:5], v[44:45], off offset:2048
	v_mov_b32_e32 v50, 0
	v_mov_b32_e32 v52, 0
	v_mov_b32_e32 v53, 0
	v_mov_b32_e32 v54, 0
	v_mov_b32_e32 v55, 0
	v_mov_b32_e32 v56, 0
	v_mov_b32_e32 v57, 0
	v_mov_b32_e32 v44, 0
	v_mov_b32_e32 v45, 0
	v_mov_b32_e32 v230, 0
	v_mov_b32_e32 v231, 0
	v_mov_b32_e32 v232, 0
	v_mov_b32_e32 v233, 0
	v_mov_b32_e32 v234, 0
	v_mov_b32_e32 v235, 0
	v_mov_b32_e32 v236, 0
	v_mov_b32_e32 v237, 0
	s_and_saveexec_b64 s[10:11], s[6:7]
	s_cbranch_execz .LBB0_314
	v_lshl_add_u64 v[42:43], v[42:43], 0, v[0:1]
	global_load_dwordx4 v[230:233], v[42:43], off offset:2048

; DI float bf2f(bf16 b) { return __uint_as_float(((unsigned)b) << 16); }
; DI float siluf_(float x) { return x / (1.f + __expf(-x)); }
; DI void phase_gdn_prep(const Ctx& c) {
;     ...
;       const int col = part * 512 + lane * 8;
;       float cur[8], prv[8], nxt[8], v[8];
;       unpack8(*(const uint4*)(P + (size_t)tok * 1536 + col), cur);
;       if (n > 0) unpack8(*(const uint4*)(P + (size_t)(tok - 1) * 1536 + col), prv);
;       else { for (int e = 0; e < 8; ++e) prv[e] = 0.f; }
;       if (n < L - 1) unpack8(*(const uint4*)(P + (size_t)(tok + 1) * 1536 + col), nxt);
;       else { for (int e = 0; e < 8; ++e) nxt[e] = 0.f; }
;       float ss = 0.f;
; #pragma unroll
;       for (int e = 0; e < 8; ++e) {
;         const float x = prv[e] * cw[col + e] + cur[e] * cw[1536 + col + e] + nxt[e] * cw[3072 + col + e];
;         v[e] = siluf_(x); ss += v[e] * v[e];
;       }
;       if (part < 2) {
;         ss += __shfl_xor(ss, 1); ss += __shfl_xor(ss, 2); ss += __shfl_xor(ss, 4); ss += __shfl_xor(ss, 8);
;         float inv = rsqrtf(ss + EPS);
;         if (part == 0) inv *= 0.08838834764831845f;
; #pragma unroll
;         for (int e = 0; e < 8; ++e) v[e] *= inv;
;       }
;       bf16* dst = (bf16*)(c.ws + OFF_GQ + (size_t)part * SZ_T512) + (size_t)tok * 512 + lane * 8;
;       *(uint4*)dst = pack8(v);
;     }
;     if (lane < 8) {
;       const float braw = bf2f(Pba[(size_t)tok * 256 + lane]);
;       const float araw = bf2f(Pba[(size_t)tok * 256 + 8 + lane]);
;       BETA[(size_t)tok * 8 + lane] = 1.f / (1.f + __expf(-braw));
;       const float x = araw + dt_b[lane];
;       const float sp = fmaxf(x, 0.f) + __logf(1.f + __expf(-fabsf(x)));
;       G[(size_t)tok * 8 + lane] = -__expf(a_log[lane]) * sp;
;     }
.LBB0_316:
	s_or_b64 exec, exec, s[6:7]
	global_load_dwordx4 v[62:65], v[30:31], off
	global_load_dwordx4 v[68:71], v[30:31], off offset:16
	global_load_dwordx4 v[72:75], v[28:29], off
	global_load_dwordx4 v[76:79], v[28:29], off offset:16
	global_load_dwordx4 v[80:83], v[32:33], off
	global_load_dwordx4 v[84:87], v[32:33], off offset:16
	s_waitcnt vmcnt(6)
	v_lshlrev_b32_e32 v52, 16, v230
	v_and_b32_e32 v53, 0xffff0000, v230
	v_lshlrev_b32_e32 v54, 16, v231
	v_and_b32_e32 v55, 0xffff0000, v231
	v_lshlrev_b32_e32 v56, 16, v232
	v_and_b32_e32 v57, 0xffff0000, v232
	v_lshlrev_b32_e32 v44, 16, v233
	v_and_b32_e32 v45, 0xffff0000, v233
	v_lshlrev_b32_e32 v50, 16, v234
	v_and_b32_e32 v51, 0xffff0000, v234
	v_lshlrev_b32_e32 v58, 16, v235
	v_and_b32_e32 v59, 0xffff0000, v235
	v_lshlrev_b32_e32 v60, 16, v236
	v_and_b32_e32 v61, 0xffff0000, v236
	v_lshlrev_b32_e32 v42, 16, v237
	v_and_b32_e32 v43, 0xffff0000, v237
	v_lshlrev_b32_e32 v46, 16, v2
	v_and_b32_e32 v47, 0xffff0000, v2
	v_lshlrev_b32_e32 v2, 16, v3
	v_and_b32_e32 v3, 0xffff0000, v3
	v_lshlrev_b32_e32 v88, 16, v4
	v_and_b32_e32 v89, 0xffff0000, v4
	v_lshlrev_b32_e32 v4, 16, v5
	v_and_b32_e32 v5, 0xffff0000, v5
	v_lshl_add_u64 v[48:49], v[38:39], 0, v[48:49]
	s_waitcnt vmcnt(5)
	v_pk_mul_f32 v[46:47], v[62:63], v[46:47]
	v_pk_mul_f32 v[2:3], v[64:65], v[2:3]
	s_waitcnt vmcnt(3)
	v_pk_fma_f32 v[46:47], v[52:53], v[72:73], v[46:47]
	v_pk_fma_f32 v[2:3], v[54:55], v[74:75], v[2:3]
	s_waitcnt vmcnt(1)
	v_pk_fma_f32 v[46:47], v[50:51], v[80:81], v[46:47]
	v_pk_fma_f32 v[50:51], v[58:59], v[82:83], v[2:3]
	v_mul_f32_e32 v0, 0xbfb8aa3b, v47
	v_mul_f32_e32 v2, 0xbfb8aa3b, v46
	v_exp_f32_e32 v3, v0
	v_exp_f32_e32 v2, v2
	v_pk_mul_f32 v[62:63], v[68:69], v[88:89]
	v_mul_f32_e32 v54, 0xbfb8aa3b, v51
	v_pk_fma_f32 v[52:53], v[56:57], v[76:77], v[62:63]
	v_mul_f32_e32 v56, 0xbfb8aa3b, v50
	v_exp_f32_e32 v55, v54
	v_exp_f32_e32 v54, v56
	v_pk_add_f32 v[2:3], v[2:3], 1.0 op_sel_hi:[1,0]
	s_waitcnt vmcnt(0)
	v_pk_fma_f32 v[52:53], v[60:61], v[84:85], v[52:53]
	v_mul_f32_e32 v57, 0xbfb8aa3b, v53
	v_mul_f32_e32 v58, 0xbfb8aa3b, v52
	v_exp_f32_e32 v57, v57
	v_exp_f32_e32 v56, v58
	v_pk_add_f32 v[54:55], v[54:55], 1.0 op_sel_hi:[1,0]
	v_pk_add_f32 v[56:57], v[56:57], 1.0 op_sel_hi:[1,0]
	v_min_f32_e32 v230, 0x7f7fffff, v3
	v_rcp_f32_e32 v231, v230
	s_nop 0
	v_fma_f32 v232, -v230, v231, 1.0
	v_fma_f32 v231, v232, v231, v231
	v_mul_f32_e32 v0, v47, v231
	v_min_f32_e32 v230, 0x7f7fffff, v2
	v_rcp_f32_e32 v231, v230
	s_nop 0
	v_fma_f32 v232, -v230, v231, 1.0
	v_fma_f32 v231, v232, v231, v231
	v_mul_f32_e32 v2, v46, v231
	v_pk_mul_f32 v[4:5], v[70:71], v[4:5]
	v_pk_fma_f32 v[4:5], v[44:45], v[78:79], v[4:5]
	v_pk_fma_f32 v[42:43], v[42:43], v[86:87], v[4:5]
	v_cvt_pk_bf16_f32 v2, v2, v0
	v_min_f32_e32 v230, 0x7f7fffff, v55
	v_rcp_f32_e32 v231, v230
	s_nop 0
	v_fma_f32 v232, -v230, v231, 1.0
	v_fma_f32 v231, v232, v231, v231
	v_mul_f32_e32 v0, v51, v231
	v_mul_f32_e32 v4, 0xbfb8aa3b, v43
	v_min_f32_e32 v230, 0x7f7fffff, v54
	v_rcp_f32_e32 v231, v230
	s_nop 0
	v_fma_f32 v232, -v230, v231, 1.0
	v_fma_f32 v231, v232, v231, v231
	v_mul_f32_e32 v3, v50, v231
	v_exp_f32_e32 v5, v4
	v_mul_f32_e32 v4, 0xbfb8aa3b, v42
	v_cvt_pk_bf16_f32 v3, v3, v0
	v_exp_f32_e32 v4, v4
	s_nop 0
	v_pk_add_f32 v[44:45], v[4:5], 1.0 op_sel_hi:[1,0]
	v_min_f32_e32 v230, 0x7f7fffff, v57
	v_rcp_f32_e32 v231, v230
	s_nop 0
	v_fma_f32 v232, -v230, v231, 1.0
	v_fma_f32 v231, v232, v231, v231
	v_mul_f32_e32 v0, v53, v231
	v_min_f32_e32 v230, 0x7f7fffff, v56
	v_rcp_f32_e32 v231, v230
	s_nop 0
	v_fma_f32 v232, -v230, v231, 1.0
	v_fma_f32 v231, v232, v231, v231
	v_mul_f32_e32 v4, v52, v231
	v_cvt_pk_bf16_f32 v4, v4, v0
	v_min_f32_e32 v230, 0x7f7fffff, v45
	v_rcp_f32_e32 v231, v230
	s_nop 0
	v_fma_f32 v232, -v230, v231, 1.0
	v_fma_f32 v231, v232, v231, v231
	v_mul_f32_e32 v0, v43, v231
	v_min_f32_e32 v230, 0x7f7fffff, v44
	v_rcp_f32_e32 v231, v230
	s_nop 0
	v_fma_f32 v232, -v230, v231, 1.0
	v_fma_f32 v231, v232, v231, v231
	v_mul_f32_e32 v5, v42, v231
	v_cvt_pk_bf16_f32 v5, v5, v0
	global_store_dwordx4 v[48:49], v[2:5], off
	s_and_saveexec_b64 s[6:7], s[4:5]
	s_cbranch_execz .LBB0_303
	v_lshlrev_b64 v[2:3], 9, v[6:7]
	v_lshl_add_u64 v[2:3], v[12:13], 0, v[2:3]
	global_load_ushort v0, v[2:3], off
	global_load_ushort v42, v[2:3], off offset:16
	v_lshlrev_b64 v[2:3], 5, v[6:7]
	v_lshl_or_b32 v2, v8, 2, v2
	s_mov_b32 s10, 0x800000
	s_waitcnt vmcnt(1)
	v_lshlrev_b32_e32 v0, 16, v0
	v_mul_f32_e32 v0, 0xbfb8aa3b, v0
	v_exp_f32_e32 v0, v0
	s_nop 0
	v_add_f32_e32 v0, 1.0, v0
	v_div_scale_f32 v7, s[8:9], v0, v0, 1.0
	v_rcp_f32_e32 v43, v7
	v_div_scale_f32 v44, vcc, 1.0, v0, 1.0
	v_readlane_b32 s8, v228, 22
	v_fma_f32 v45, -v7, v43, 1.0
	v_fmac_f32_e32 v43, v45, v43
	v_mul_f32_e32 v45, v44, v43
	v_fma_f32 v46, -v7, v45, v44
	v_fmac_f32_e32 v45, v46, v43
	v_fma_f32 v7, -v7, v45, v44
	v_readlane_b32 s9, v228, 23
	v_div_fmas_f32 v7, v7, v43, v45
	v_div_fixup_f32 v0, v7, v0, 1.0
	v_lshl_add_u64 v[4:5], s[8:9], 0, v[2:3]
	global_store_dword v[4:5], v0, off
	global_load_dword v0, v[14:15], off
	s_nop 0
	global_load_dword v4, v[16:17], off
	s_waitcnt vmcnt(3)
	v_lshlrev_b32_e32 v5, 16, v42
	s_mov_b32 s8, 0xbfb8aa3b
	s_mov_b32 s9, 0x7f800000
	s_waitcnt vmcnt(1)
	v_add_f32_e32 v0, v0, v5
	v_mul_f32_e64 v5, |v0|, s8
	v_exp_f32_e32 v5, v5
	s_mov_b32 s8, 0x3f317217
	s_waitcnt vmcnt(0)
	v_mul_f32_e32 v4, 0x3fb8aa3b, v4
	v_exp_f32_e32 v4, v4
	v_add_f32_e32 v5, 1.0, v5
	v_cmp_gt_f32_e32 vcc, s10, v5
	v_max_f32_e32 v0, 0, v0
	s_nop 0
	v_cndmask_b32_e64 v7, 0, 32, vcc
	v_ldexp_f32 v5, v5, v7
	v_log_f32_e32 v5, v5
	v_cndmask_b32_e32 v7, 0, v191, vcc
	v_mul_f32_e32 v42, 0x3f317217, v5
	v_fma_f32 v42, v5, s8, -v42
	v_fmac_f32_e32 v42, 0x3377d1cf, v5
	v_fmac_f32_e32 v42, 0x3f317217, v5
	v_cmp_lt_f32_e64 vcc, |v5|, s9
	v_readlane_b32 s8, v228, 24
	v_readlane_b32 s9, v228, 25
	v_cndmask_b32_e32 v5, v5, v42, vcc
	v_sub_f32_e32 v5, v5, v7
	v_add_f32_e32 v0, v0, v5
	v_mul_f32_e64 v0, v0, -v4
	v_lshl_add_u64 v[2:3], s[8:9], 0, v[2:3]
	global_store_dword v[2:3], v0, off
	s_branch .LBB0_303
